# P7 in-lane 4-row complex Horner and group-weight multiply as in-place scalar v_fma_f32 (drops 32 v_mov shuffles and the packed FMAs)
# baseline (speedup 1.0000x reference)
; template <int DIR>
; __device__ __forceinline__ void s5_local_dir(const bf16_t* UZ, unsigned char* ws, int gw, int NGW, int lane) {
;     ...
;             f32x2 s2 = {DIR ? cr[3] : cr[0], DIR ? ci[3] : ci[0]};
; #pragma unroll
;             for (int ii = 1; ii < 4; ++ii) { const int i = DIR ? 3 - ii : ii;
;                 s2 = cmac(s2, (f32x2){a1r[t], a1r[t]}, (f32x2){-a1i[t], a1i[t]}, (f32x2){cr[i], ci[i]}); }
;             s2 = cmac(s2, (f32x2){wr_[t], wr_[t]}, (f32x2){-wi_[t], wi_[t]}, (f32x2){0.f, 0.f});
;             float sr = s2.x, si = s2.y;
;             sr += __shfl_xor(sr, 16); si += __shfl_xor(si, 16); sr += __shfl_xor(sr, 32); si += __shfl_xor(si, 32);
;             if (fq == 0) { e[16 * t + fr] = Rr[t]; e[64 + 16 * t + fr] = Ri[t]; }
;             const float nr = fmaf(a64r[t], Rr[t], fmaf(-a64i[t], Ri[t], sr)), ni = fmaf(a64r[t], Ri[t], fmaf(a64i[t], Rr[t], si)); Rr[t] = nr; Ri[t] = ni;
;         }
;     }
.LBB0_652:
	global_store_dword v[116:117], v240, off offset:-256
	global_store_dword v[116:117], v241, off
	s_waitcnt vmcnt(9)
	v_mfma_f32_16x16x32_bf16 v[140:143], v[108:111], v[26:29], 0
	v_mfma_f32_16x16x32_bf16 v[144:147], v[108:111], v[34:37], 0
	v_mfma_f32_16x16x32_bf16 v[196:199], v[108:111], v[48:51], 0
	v_mfma_f32_16x16x32_bf16 v[200:203], v[108:111], v[56:59], 0
	v_mfma_f32_16x16x32_bf16 v[208:211], v[108:111], v[70:73], 0
	v_mfma_f32_16x16x32_bf16 v[212:215], v[108:111], v[78:81], 0
	v_mfma_f32_16x16x32_bf16 v[228:231], v[108:111], v[92:95], 0
	v_mfma_f32_16x16x32_bf16 v[184:187], v[108:111], v[100:103], 0
	v_mfma_f32_16x16x32_bf16 v[140:143], v[112:115], v[30:33], v[140:143]
	v_mfma_f32_16x16x32_bf16 v[144:147], v[112:115], v[38:41], v[144:147]
	v_mfma_f32_16x16x32_bf16 v[196:199], v[112:115], v[52:55], v[196:199]
	v_mfma_f32_16x16x32_bf16 v[200:203], v[112:115], v[60:63], v[200:203]
	v_mfma_f32_16x16x32_bf16 v[208:211], v[112:115], v[74:77], v[208:211]
	v_mfma_f32_16x16x32_bf16 v[212:215], v[112:115], v[82:85], v[212:215]
	v_mfma_f32_16x16x32_bf16 v[228:231], v[112:115], v[96:99], v[228:231]
	v_mfma_f32_16x16x32_bf16 v[184:187], v[112:115], v[104:107], v[184:187]
	s_nop 6
	v_fma_f32 v142, v20, v143, v142
	v_fma_f32 v198, v42, v199, v198
	v_fma_f32 v210, v64, v211, v210
	v_fma_f32 v230, v86, v231, v230
	v_fma_f32 v146, v21, v147, v146
	v_fma_f32 v202, v43, v203, v202
	v_fma_f32 v214, v65, v215, v214
	v_fma_f32 v186, v87, v187, v186
	v_fma_f32 v142, v0, v147, v142
	v_fma_f32 v198, v4, v203, v198
	v_fma_f32 v210, v8, v215, v210
	v_fma_f32 v230, v12, v187, v230
	v_fma_f32 v146, v1, v143, v146
	v_fma_f32 v202, v5, v199, v202
	v_fma_f32 v214, v9, v211, v214
	v_fma_f32 v186, v13, v231, v186
	v_fma_f32 v141, v20, v142, v141
	v_fma_f32 v197, v42, v198, v197
	v_fma_f32 v209, v64, v210, v209
	v_fma_f32 v229, v86, v230, v229
	v_fma_f32 v145, v21, v146, v145
	v_fma_f32 v201, v43, v202, v201
	v_fma_f32 v213, v65, v214, v213
	v_fma_f32 v185, v87, v186, v185
	v_fma_f32 v141, v0, v146, v141
	v_fma_f32 v197, v4, v202, v197
	v_fma_f32 v209, v8, v214, v209
	v_fma_f32 v229, v12, v186, v229
	v_fma_f32 v145, v1, v142, v145
	v_fma_f32 v201, v5, v198, v201
	v_fma_f32 v213, v9, v210, v213
	v_fma_f32 v185, v13, v230, v185
	v_fma_f32 v140, v20, v141, v140
	v_fma_f32 v196, v42, v197, v196
	v_fma_f32 v208, v64, v209, v208
	v_fma_f32 v228, v86, v229, v228
	v_fma_f32 v144, v21, v145, v144
	v_fma_f32 v200, v43, v201, v200
	v_fma_f32 v212, v65, v213, v212
	v_fma_f32 v184, v87, v185, v184
	v_fma_f32 v140, v0, v145, v140
	v_fma_f32 v196, v4, v201, v196
	v_fma_f32 v208, v8, v213, v208
	v_fma_f32 v228, v12, v185, v228
	v_fma_f32 v144, v1, v141, v144
	v_fma_f32 v200, v5, v197, v200
	v_fma_f32 v212, v9, v209, v212
	v_fma_f32 v184, v13, v229, v184
	v_mul_f32_e32 v142, v22, v140
	v_mul_f32_e32 v198, v44, v196
	v_mul_f32_e32 v210, v66, v208
	v_mul_f32_e32 v229, v88, v228
	v_mul_f32_e32 v141, v23, v144
	v_mul_f32_e32 v197, v45, v200
	v_mul_f32_e32 v209, v67, v212
	v_mul_f32_e32 v230, v89, v184
	v_fma_f32 v141, v25, v140, v141
	v_fma_f32 v197, v47, v196, v197
	v_fma_f32 v209, v69, v208, v209
	v_fma_f32 v185, v91, v228, v230
	v_fma_f32 v140, v24, v144, v142
	v_fma_f32 v196, v46, v200, v198
	v_fma_f32 v208, v68, v212, v210
	v_fma_f32 v184, v90, v184, v229
	s_nop 1
	v_permlane32_swap_b32_e32 v140, v208
	v_permlane32_swap_b32_e32 v141, v209
	v_permlane32_swap_b32_e32 v196, v184
	v_permlane32_swap_b32_e32 v197, v185
	v_add_f32_e32 v140, v140, v208
	v_add_f32_e32 v196, v196, v184
	v_add_f32_e32 v141, v141, v209
	v_add_f32_e32 v197, v197, v185
	s_nop 0
	v_permlane16_swap_b32_e32 v140, v196
	v_permlane16_swap_b32_e32 v141, v197
	v_add_f32_e32 v140, v140, v196
	v_add_f32_e32 v141, v141, v197
	v_fma_f32 v244, -v243, v241, v140
	v_fma_f32 v245, v243, v240, v141
	v_fma_f32 v240, v242, v240, v244
	v_fma_f32 v241, v242, v241, v245
	v_lshl_add_u64 v[116:117], v[116:117], 0, s[2:3]
	v_subrev_u32_e32 v16, 64, v16
	s_and_b64 vcc, exec, s[36:37]
	s_cbranch_vccnz .LBB0_684
	s_mov_b32 s38, s49
	s_waitcnt vmcnt(3)
	v_mov_b32_e32 v110, v118
	v_mov_b32_e32 v111, v119
	s_waitcnt vmcnt(2)
	v_mov_b32_e32 v112, v120
	v_mov_b32_e32 v113, v121
	s_waitcnt vmcnt(1)
	v_mov_b32_e32 v114, v122
	v_mov_b32_e32 v115, v123
	s_waitcnt vmcnt(0)
	v_mov_b32_e32 v108, v124
	v_mov_b32_e32 v109, v125
	s_branch .LBB0_649

; template <int DIR>
; __device__ __forceinline__ void s5_local_dir(const bf16_t* UZ, unsigned char* ws, int gw, int NGW, int lane) {
;     ...
;             f32x2 s2 = {DIR ? cr[3] : cr[0], DIR ? ci[3] : ci[0]};
; #pragma unroll
;             for (int ii = 1; ii < 4; ++ii) { const int i = DIR ? 3 - ii : ii;
;                 s2 = cmac(s2, (f32x2){a1r[t], a1r[t]}, (f32x2){-a1i[t], a1i[t]}, (f32x2){cr[i], ci[i]}); }
;             s2 = cmac(s2, (f32x2){wr_[t], wr_[t]}, (f32x2){-wi_[t], wi_[t]}, (f32x2){0.f, 0.f});
;             float sr = s2.x, si = s2.y;
;             sr += __shfl_xor(sr, 16); si += __shfl_xor(si, 16); sr += __shfl_xor(sr, 32); si += __shfl_xor(si, 32);
;             if (fq == 0) { e[16 * t + fr] = Rr[t]; e[64 + 16 * t + fr] = Ri[t]; }
;             const float nr = fmaf(a64r[t], Rr[t], fmaf(-a64i[t], Ri[t], sr)), ni = fmaf(a64r[t], Ri[t], fmaf(a64i[t], Rr[t], si)); Rr[t] = nr; Ri[t] = ni;
;         }
;     }
.LBB0_674:
	global_store_dword v[116:117], v240, off offset:-256
	global_store_dword v[116:117], v241, off
	s_waitcnt vmcnt(9)
	v_mfma_f32_16x16x32_bf16 v[136:139], v[108:111], v[26:29], 0
	v_mfma_f32_16x16x32_bf16 v[140:143], v[108:111], v[34:37], 0
	v_mfma_f32_16x16x32_bf16 v[196:199], v[108:111], v[48:51], 0
	v_mfma_f32_16x16x32_bf16 v[200:203], v[108:111], v[56:59], 0
	v_mfma_f32_16x16x32_bf16 v[208:211], v[108:111], v[70:73], 0
	v_mfma_f32_16x16x32_bf16 v[212:215], v[108:111], v[78:81], 0
	v_mfma_f32_16x16x32_bf16 v[224:227], v[108:111], v[88:91], 0
	v_mfma_f32_16x16x32_bf16 v[184:187], v[108:111], v[100:103], 0
	v_mfma_f32_16x16x32_bf16 v[136:139], v[112:115], v[30:33], v[136:139]
	v_mfma_f32_16x16x32_bf16 v[140:143], v[112:115], v[38:41], v[140:143]
	v_mfma_f32_16x16x32_bf16 v[196:199], v[112:115], v[52:55], v[196:199]
	v_mfma_f32_16x16x32_bf16 v[200:203], v[112:115], v[60:63], v[200:203]
	v_mfma_f32_16x16x32_bf16 v[208:211], v[112:115], v[74:77], v[208:211]
	v_mfma_f32_16x16x32_bf16 v[212:215], v[112:115], v[82:85], v[212:215]
	v_mfma_f32_16x16x32_bf16 v[224:227], v[112:115], v[96:99], v[224:227]
	v_mfma_f32_16x16x32_bf16 v[184:187], v[112:115], v[104:107], v[184:187]
	s_nop 6
	v_fma_f32 v137, v18, v136, v137
	v_fma_f32 v197, v42, v196, v197
	v_fma_f32 v209, v64, v208, v209
	v_fma_f32 v225, v86, v224, v225
	v_fma_f32 v141, v19, v140, v141
	v_fma_f32 v201, v43, v200, v201
	v_fma_f32 v213, v65, v212, v213
	v_fma_f32 v185, v87, v184, v185
	v_fma_f32 v137, v0, v140, v137
	v_fma_f32 v197, v4, v200, v197
	v_fma_f32 v209, v8, v212, v209
	v_fma_f32 v225, v12, v184, v225
	v_fma_f32 v141, v1, v136, v141
	v_fma_f32 v201, v5, v196, v201
	v_fma_f32 v213, v9, v208, v213
	v_fma_f32 v185, v13, v224, v185
	v_fma_f32 v138, v18, v137, v138
	v_fma_f32 v198, v42, v197, v198
	v_fma_f32 v210, v64, v209, v210
	v_fma_f32 v226, v86, v225, v226
	v_fma_f32 v142, v19, v141, v142
	v_fma_f32 v202, v43, v201, v202
	v_fma_f32 v214, v65, v213, v214
	v_fma_f32 v186, v87, v185, v186
	v_fma_f32 v138, v0, v141, v138
	v_fma_f32 v198, v4, v201, v198
	v_fma_f32 v210, v8, v213, v210
	v_fma_f32 v226, v12, v185, v226
	v_fma_f32 v142, v1, v137, v142
	v_fma_f32 v202, v5, v197, v202
	v_fma_f32 v214, v9, v209, v214
	v_fma_f32 v186, v13, v225, v186
	v_fma_f32 v139, v18, v138, v139
	v_fma_f32 v199, v42, v198, v199
	v_fma_f32 v211, v64, v210, v211
	v_fma_f32 v227, v86, v226, v227
	v_fma_f32 v143, v19, v142, v143
	v_fma_f32 v203, v43, v202, v203
	v_fma_f32 v215, v65, v214, v215
	v_fma_f32 v187, v87, v186, v187
	v_fma_f32 v139, v0, v142, v139
	v_fma_f32 v199, v4, v202, v199
	v_fma_f32 v211, v8, v214, v211
	v_fma_f32 v227, v12, v186, v227
	v_fma_f32 v143, v1, v138, v143
	v_fma_f32 v203, v5, v198, v203
	v_fma_f32 v215, v9, v210, v215
	v_fma_f32 v187, v13, v226, v187
	v_mul_f32_e32 v136, v22, v139
	v_mul_f32_e32 v196, v44, v199
	v_mul_f32_e32 v208, v66, v211
	v_mul_f32_e32 v224, v92, v227
	v_mul_f32_e32 v137, v23, v143
	v_mul_f32_e32 v197, v45, v203
	v_mul_f32_e32 v209, v67, v215
	v_mul_f32_e32 v225, v93, v187
	v_fma_f32 v137, v25, v139, v137
	v_fma_f32 v197, v47, v199, v197
	v_fma_f32 v209, v69, v211, v209
	v_fma_f32 v185, v95, v227, v225
	v_fma_f32 v136, v24, v143, v136
	v_fma_f32 v196, v46, v203, v196
	v_fma_f32 v208, v68, v215, v208
	v_fma_f32 v184, v94, v187, v224
	s_nop 1
	v_permlane32_swap_b32_e32 v136, v208
	v_permlane32_swap_b32_e32 v137, v209
	v_permlane32_swap_b32_e32 v196, v184
	v_permlane32_swap_b32_e32 v197, v185
	v_add_f32_e32 v136, v136, v208
	v_add_f32_e32 v196, v196, v184
	v_add_f32_e32 v137, v137, v209
	v_add_f32_e32 v197, v197, v185
	s_nop 0
	v_permlane16_swap_b32_e32 v136, v196
	v_permlane16_swap_b32_e32 v137, v197
	v_add_f32_e32 v136, v136, v196
	v_add_f32_e32 v137, v137, v197
	v_fma_f32 v244, -v243, v241, v136
	v_fma_f32 v245, v243, v240, v137
	v_fma_f32 v240, v242, v240, v244
	v_fma_f32 v241, v242, v241, v245
	v_lshl_add_u64 v[116:117], v[116:117], 0, s[4:5]
	v_add_u32_e32 v20, 64, v20
	s_and_b64 vcc, exec, s[22:23]
	s_cbranch_vccnz .LBB0_702
	s_mov_b32 s24, s40
	s_waitcnt vmcnt(3)
	v_mov_b32_e32 v108, v118
	v_mov_b32_e32 v109, v119
	s_waitcnt vmcnt(2)
	v_mov_b32_e32 v112, v120
	v_mov_b32_e32 v113, v121
	s_waitcnt vmcnt(1)
	v_mov_b32_e32 v114, v122
	v_mov_b32_e32 v115, v123
	s_waitcnt vmcnt(0)
	v_mov_b32_e32 v110, v124
	v_mov_b32_e32 v111, v125
	s_branch .LBB0_671
